# combined variant plus FFN-up sample-unit drain chunks with batched LDS reads
# speedup vs baseline: 1.0075x; 1.0037x over previous
; template <class Epi>
; __device__ __forceinline__ void mini_ring(PG8_LAS unsigned char* lds, const bf16_t* A, const bf16_t* Bt, int K, const Epi& E, int mu, int wave_u) {
;     ...
;     asm volatile("s_waitcnt vmcnt(10)" ::: "memory"); __builtin_amdgcn_s_barrier(); asm volatile("" ::: "memory"); MR_CONSUME(nmain);
;     asm volatile("s_waitcnt vmcnt(8)" ::: "memory"); __builtin_amdgcn_s_barrier(); asm volatile("" ::: "memory"); MR_CONSUME(nmain + 1);
;     asm volatile("s_waitcnt vmcnt(6)" ::: "memory"); __builtin_amdgcn_s_barrier(); asm volatile("" ::: "memory"); MR_CONSUME(nmain + 2);
;     asm volatile("s_waitcnt vmcnt(4)" ::: "memory"); __builtin_amdgcn_s_barrier(); asm volatile("" ::: "memory"); MR_CONSUME(nmain + 3);
;     asm volatile("s_waitcnt vmcnt(2)" ::: "memory"); __builtin_amdgcn_s_barrier(); asm volatile("" ::: "memory"); MR_CONSUME(nmain + 4);
;     asm volatile("s_waitcnt vmcnt(0)" ::: "memory"); __builtin_amdgcn_s_barrier(); asm volatile("" ::: "memory"); MR_CONSUME(nmain + 5);
.LBB0_1217:
	s_waitcnt vmcnt(10)
	s_barrier
	v_add_u32_e32 v14, 0, v21
	v_add_u32_e32 v0, 0, v22
	s_and_b64 vcc, exec, s[16:17]
	v_add_u32_e32 v17, v14, v20
	v_add_u32_e32 v16, v14, v19
	v_add_u32_e32 v15, v0, v20
	v_add_u32_e32 v14, v0, v19
	s_cbranch_vccz .LBB0_1219
	ds_read_b128 v[28:31], v17 offset:32768
	ds_read_b128 v[24:27], v15 offset:40960
	ds_read_b128 v[36:39], v15 offset:43008
	ds_read_b128 v[52:55], v15 offset:45056
	ds_read_b128 v[60:63], v15 offset:47104
	ds_read_b128 v[32:35], v16 offset:32768
	ds_read_b128 v[64:67], v14 offset:40960
	s_waitcnt lgkmcnt(5)
	v_mfma_f32_16x16x32_bf16 v[46:49], v[24:27], v[28:31], v[46:49]
	ds_read_b128 v[24:27], v14 offset:43008
	s_waitcnt lgkmcnt(5)
	v_mfma_f32_16x16x32_bf16 v[10:13], v[36:39], v[28:31], v[10:13]
	ds_read_b128 v[36:39], v14 offset:45056
	s_waitcnt lgkmcnt(5)
	v_mfma_f32_16x16x32_bf16 v[6:9], v[52:55], v[28:31], v[6:9]
	ds_read_b128 v[52:55], v14 offset:47104
	s_waitcnt lgkmcnt(5)
	v_mfma_f32_16x16x32_bf16 v[2:5], v[60:63], v[28:31], v[2:5]
	s_waitcnt lgkmcnt(3)
	v_mfma_f32_16x16x32_bf16 v[46:49], v[64:67], v[32:35], v[46:49]
	s_waitcnt lgkmcnt(2)
	v_mfma_f32_16x16x32_bf16 v[10:13], v[24:27], v[32:35], v[10:13]
	s_waitcnt lgkmcnt(1)
	v_mfma_f32_16x16x32_bf16 v[6:9], v[36:39], v[32:35], v[6:9]
	s_waitcnt lgkmcnt(0)
	v_mfma_f32_16x16x32_bf16 v[2:5], v[52:55], v[32:35], v[2:5]
.LBB0_1219:
	s_waitcnt vmcnt(8)
	s_barrier
	s_and_b64 vcc, exec, s[10:11]
	s_cbranch_vccnz .LBB0_1221
	ds_read_b128 v[28:31], v17 offset:49152
	ds_read_b128 v[24:27], v15 offset:57344
	ds_read_b128 v[36:39], v15 offset:59392
	ds_read_b128 v[52:55], v15 offset:61440
	ds_read_b128 v[60:63], v15 offset:63488
	ds_read_b128 v[32:35], v16 offset:49152
	ds_read_b128 v[64:67], v14 offset:57344
	s_waitcnt lgkmcnt(5)
	v_mfma_f32_16x16x32_bf16 v[46:49], v[24:27], v[28:31], v[46:49]
	ds_read_b128 v[24:27], v14 offset:59392
	s_waitcnt lgkmcnt(5)
	v_mfma_f32_16x16x32_bf16 v[10:13], v[36:39], v[28:31], v[10:13]
	ds_read_b128 v[36:39], v14 offset:61440
	s_waitcnt lgkmcnt(5)
	v_mfma_f32_16x16x32_bf16 v[6:9], v[52:55], v[28:31], v[6:9]
	ds_read_b128 v[52:55], v14 offset:63488
	s_waitcnt lgkmcnt(5)
	v_mfma_f32_16x16x32_bf16 v[2:5], v[60:63], v[28:31], v[2:5]
	s_waitcnt lgkmcnt(3)
	v_mfma_f32_16x16x32_bf16 v[46:49], v[64:67], v[32:35], v[46:49]
	s_waitcnt lgkmcnt(2)
	v_mfma_f32_16x16x32_bf16 v[10:13], v[24:27], v[32:35], v[10:13]
	s_waitcnt lgkmcnt(1)
	v_mfma_f32_16x16x32_bf16 v[6:9], v[36:39], v[32:35], v[6:9]
	s_waitcnt lgkmcnt(0)
	v_mfma_f32_16x16x32_bf16 v[2:5], v[52:55], v[32:35], v[2:5]
.LBB0_1221:
	s_waitcnt vmcnt(6)
	s_barrier
	s_and_b64 vcc, exec, s[10:11]
	s_cbranch_vccnz .LBB0_1223
	s_mov_b32 s0, 0x10000
	v_add_u32_e32 v23, s0, v15
	v_add_u32_e32 v0, s0, v14
	v_add_u32_e32 v28, s0, v17
	v_add_u32_e32 v40, s0, v16
	ds_read_b128 v[28:31], v28
	ds_read_b128 v[24:27], v23 offset:8192
	ds_read_b128 v[36:39], v23 offset:10240
	ds_read_b128 v[52:55], v23 offset:12288
	ds_read_b128 v[60:63], v23 offset:14336
	ds_read_b128 v[32:35], v40
	ds_read_b128 v[64:67], v0 offset:8192
	s_waitcnt lgkmcnt(5)
	v_mfma_f32_16x16x32_bf16 v[46:49], v[24:27], v[28:31], v[46:49]
	ds_read_b128 v[24:27], v0 offset:10240
	s_waitcnt lgkmcnt(5)
	v_mfma_f32_16x16x32_bf16 v[10:13], v[36:39], v[28:31], v[10:13]
	ds_read_b128 v[36:39], v0 offset:12288
	s_waitcnt lgkmcnt(5)
	v_mfma_f32_16x16x32_bf16 v[6:9], v[52:55], v[28:31], v[6:9]
	ds_read_b128 v[52:55], v0 offset:14336
	s_waitcnt lgkmcnt(5)
	v_mfma_f32_16x16x32_bf16 v[2:5], v[60:63], v[28:31], v[2:5]
	s_waitcnt lgkmcnt(3)
	v_mfma_f32_16x16x32_bf16 v[46:49], v[64:67], v[32:35], v[46:49]
	s_waitcnt lgkmcnt(2)
	v_mfma_f32_16x16x32_bf16 v[10:13], v[24:27], v[32:35], v[10:13]
	s_waitcnt lgkmcnt(1)
	v_mfma_f32_16x16x32_bf16 v[6:9], v[36:39], v[32:35], v[6:9]
	s_waitcnt lgkmcnt(0)
	v_mfma_f32_16x16x32_bf16 v[2:5], v[52:55], v[32:35], v[2:5]
; template <class Epi>
; __device__ __forceinline__ void mini_ring(PG8_LAS unsigned char* lds, const bf16_t* A, const bf16_t* Bt, int K, const Epi& E, int mu, int wave_u) {
;     ...
;     asm volatile("s_waitcnt vmcnt(10)" ::: "memory"); __builtin_amdgcn_s_barrier(); asm volatile("" ::: "memory"); MR_CONSUME(nmain);
;     asm volatile("s_waitcnt vmcnt(8)" ::: "memory"); __builtin_amdgcn_s_barrier(); asm volatile("" ::: "memory"); MR_CONSUME(nmain + 1);
;     asm volatile("s_waitcnt vmcnt(6)" ::: "memory"); __builtin_amdgcn_s_barrier(); asm volatile("" ::: "memory"); MR_CONSUME(nmain + 2);
;     asm volatile("s_waitcnt vmcnt(4)" ::: "memory"); __builtin_amdgcn_s_barrier(); asm volatile("" ::: "memory"); MR_CONSUME(nmain + 3);
;     asm volatile("s_waitcnt vmcnt(2)" ::: "memory"); __builtin_amdgcn_s_barrier(); asm volatile("" ::: "memory"); MR_CONSUME(nmain + 4);
;     asm volatile("s_waitcnt vmcnt(0)" ::: "memory"); __builtin_amdgcn_s_barrier(); asm volatile("" ::: "memory"); MR_CONSUME(nmain + 5);
.LBB0_1223:
	s_waitcnt vmcnt(4)
	s_barrier
	s_and_b64 vcc, exec, s[10:11]
	s_cbranch_vccnz .LBB0_1225
	s_mov_b32 s0, 0x14000
	v_add_u32_e32 v23, s0, v15
	v_add_u32_e32 v0, s0, v14
	v_add_u32_e32 v28, s0, v17
	v_add_u32_e32 v40, s0, v16
	ds_read_b128 v[28:31], v28
	ds_read_b128 v[24:27], v23 offset:8192
	ds_read_b128 v[36:39], v23 offset:10240
	ds_read_b128 v[52:55], v23 offset:12288
	ds_read_b128 v[60:63], v23 offset:14336
	ds_read_b128 v[32:35], v40
	ds_read_b128 v[64:67], v0 offset:8192
	s_waitcnt lgkmcnt(5)
	v_mfma_f32_16x16x32_bf16 v[46:49], v[24:27], v[28:31], v[46:49]
	ds_read_b128 v[24:27], v0 offset:10240
	s_waitcnt lgkmcnt(5)
	v_mfma_f32_16x16x32_bf16 v[10:13], v[36:39], v[28:31], v[10:13]
	ds_read_b128 v[36:39], v0 offset:12288
	s_waitcnt lgkmcnt(5)
	v_mfma_f32_16x16x32_bf16 v[6:9], v[52:55], v[28:31], v[6:9]
	ds_read_b128 v[52:55], v0 offset:14336
	s_waitcnt lgkmcnt(5)
	v_mfma_f32_16x16x32_bf16 v[2:5], v[60:63], v[28:31], v[2:5]
	s_waitcnt lgkmcnt(3)
	v_mfma_f32_16x16x32_bf16 v[46:49], v[64:67], v[32:35], v[46:49]
	s_waitcnt lgkmcnt(2)
	v_mfma_f32_16x16x32_bf16 v[10:13], v[24:27], v[32:35], v[10:13]
	s_waitcnt lgkmcnt(1)
	v_mfma_f32_16x16x32_bf16 v[6:9], v[36:39], v[32:35], v[6:9]
	s_waitcnt lgkmcnt(0)
	v_mfma_f32_16x16x32_bf16 v[2:5], v[52:55], v[32:35], v[2:5]
.LBB0_1225:
	s_waitcnt vmcnt(2)
	s_barrier
	s_and_b64 vcc, exec, s[10:11]
	s_cbranch_vccnz .LBB0_1227
	s_mov_b32 s0, 0x18000
	v_add_u32_e32 v23, s0, v15
	v_add_u32_e32 v0, s0, v14
	v_add_u32_e32 v28, s0, v17
	v_add_u32_e32 v40, s0, v16
	ds_read_b128 v[28:31], v28
	ds_read_b128 v[24:27], v23 offset:8192
	ds_read_b128 v[36:39], v23 offset:10240
	ds_read_b128 v[52:55], v23 offset:12288
	ds_read_b128 v[60:63], v23 offset:14336
	ds_read_b128 v[32:35], v40
	ds_read_b128 v[64:67], v0 offset:8192
	s_waitcnt lgkmcnt(5)
	v_mfma_f32_16x16x32_bf16 v[46:49], v[24:27], v[28:31], v[46:49]
	ds_read_b128 v[24:27], v0 offset:10240
	s_waitcnt lgkmcnt(5)
	v_mfma_f32_16x16x32_bf16 v[10:13], v[36:39], v[28:31], v[10:13]
	ds_read_b128 v[36:39], v0 offset:12288
	s_waitcnt lgkmcnt(5)
	v_mfma_f32_16x16x32_bf16 v[6:9], v[52:55], v[28:31], v[6:9]
	ds_read_b128 v[52:55], v0 offset:14336
	s_waitcnt lgkmcnt(5)
	v_mfma_f32_16x16x32_bf16 v[2:5], v[60:63], v[28:31], v[2:5]
	s_waitcnt lgkmcnt(3)
	v_mfma_f32_16x16x32_bf16 v[46:49], v[64:67], v[32:35], v[46:49]
	s_waitcnt lgkmcnt(2)
	v_mfma_f32_16x16x32_bf16 v[10:13], v[24:27], v[32:35], v[10:13]
	s_waitcnt lgkmcnt(1)
	v_mfma_f32_16x16x32_bf16 v[6:9], v[36:39], v[32:35], v[6:9]
	s_waitcnt lgkmcnt(0)
	v_mfma_f32_16x16x32_bf16 v[2:5], v[52:55], v[32:35], v[2:5]
.LBB0_1227:
	s_waitcnt vmcnt(0)
	s_barrier
	s_and_b64 vcc, exec, s[10:11]
	s_cbranch_vccnz .LBB0_1229
	s_mov_b32 s0, 0x1c000
	v_add_u32_e32 v23, s0, v15
	v_add_u32_e32 v0, s0, v14
	v_add_u32_e32 v28, s0, v17
	v_add_u32_e32 v40, s0, v16
	ds_read_b128 v[28:31], v28
	ds_read_b128 v[24:27], v23 offset:8192
	ds_read_b128 v[36:39], v23 offset:10240
	ds_read_b128 v[52:55], v23 offset:12288
	ds_read_b128 v[60:63], v23 offset:14336
	ds_read_b128 v[32:35], v40
	ds_read_b128 v[64:67], v0 offset:8192
	s_waitcnt lgkmcnt(5)
	v_mfma_f32_16x16x32_bf16 v[46:49], v[24:27], v[28:31], v[46:49]
	ds_read_b128 v[24:27], v0 offset:10240
	s_waitcnt lgkmcnt(5)
	v_mfma_f32_16x16x32_bf16 v[10:13], v[36:39], v[28:31], v[10:13]
	ds_read_b128 v[36:39], v0 offset:12288
	s_waitcnt lgkmcnt(5)
	v_mfma_f32_16x16x32_bf16 v[6:9], v[52:55], v[28:31], v[6:9]
	ds_read_b128 v[52:55], v0 offset:14336
	s_waitcnt lgkmcnt(5)
	v_mfma_f32_16x16x32_bf16 v[2:5], v[60:63], v[28:31], v[2:5]
	s_waitcnt lgkmcnt(3)
	v_mfma_f32_16x16x32_bf16 v[46:49], v[64:67], v[32:35], v[46:49]
	s_waitcnt lgkmcnt(2)
	v_mfma_f32_16x16x32_bf16 v[10:13], v[24:27], v[32:35], v[10:13]
	s_waitcnt lgkmcnt(1)
	v_mfma_f32_16x16x32_bf16 v[6:9], v[36:39], v[32:35], v[6:9]
	s_waitcnt lgkmcnt(0)
	v_mfma_f32_16x16x32_bf16 v[2:5], v[52:55], v[32:35], v[2:5]
